# GU epilogue: packed v_pk_mul/v_pk_fma variant (38 instr per 8 outputs)
# speedup vs baseline: 1.2023x; 1.0094x over previous
.LBB0_1255:
	s_lshl_b32 s6, s48, 8
	s_add_i32 s6, s6, s91
	s_lshl_b32 s22, s49, 7
	s_ashr_i32 s23, s22, 31
	s_add_u32 s24, s2, s22
	s_addc_u32 s25, s3, s23
	s_add_u32 s24, s24, s68
	s_addc_u32 s25, s25, s69
	s_mov_b32 s98, 0x44800000
	s_mov_b32 s99, 0xbd38aa3b
	v_and_or_b32 v4, v174, 15, s6
	v_lshrrev_b32_e32 v0, 4, v174
	v_mul_lo_u32 v4, v4, s42
	v_lshl_add_u32 v4, v0, 3, v4
	v_pk_mul_f32 v[8:9], v[156:157], s[98:99] op_sel:[0,1] op_sel_hi:[1,1]
	v_pk_mul_f32 v[10:11], v[158:159], s[98:99] op_sel:[0,1] op_sel_hi:[1,1]
	v_pk_mul_f32 v[12:13], v[152:153], s[98:99] op_sel:[0,1] op_sel_hi:[1,1]
	v_pk_mul_f32 v[14:15], v[154:155], s[98:99] op_sel:[0,1] op_sel_hi:[1,1]
	v_exp_f32_e32 v8, v8
	v_exp_f32_e32 v9, v9
	v_exp_f32_e32 v10, v10
	v_exp_f32_e32 v11, v11
	v_exp_f32_e32 v12, v12
	v_exp_f32_e32 v13, v13
	v_exp_f32_e32 v14, v14
	v_exp_f32_e32 v15, v15
	v_pk_fma_f32 v[8:9], v[8:9], s[98:99], s[98:99] op_sel_hi:[1,0,0]
	v_pk_fma_f32 v[10:11], v[10:11], s[98:99], s[98:99] op_sel_hi:[1,0,0]
	v_pk_fma_f32 v[12:13], v[12:13], s[98:99], s[98:99] op_sel_hi:[1,0,0]
	v_pk_fma_f32 v[14:15], v[14:15], s[98:99], s[98:99] op_sel_hi:[1,0,0]
	v_rcp_f32_e32 v8, v8
	v_rcp_f32_e32 v9, v9
	v_rcp_f32_e32 v10, v10
	v_rcp_f32_e32 v11, v11
	v_rcp_f32_e32 v12, v12
	v_rcp_f32_e32 v13, v13
	v_rcp_f32_e32 v14, v14
	v_rcp_f32_e32 v15, v15
	v_pk_mul_f32 v[8:9], v[156:157], v[8:9]
	v_pk_mul_f32 v[10:11], v[158:159], v[10:11]
	v_pk_mul_f32 v[12:13], v[152:153], v[12:13]
	v_pk_mul_f32 v[14:15], v[154:155], v[14:15]
	v_pk_mul_f32 v[8:9], v[8:9], v[148:149]
	v_pk_mul_f32 v[10:11], v[10:11], v[150:151]
	v_pk_mul_f32 v[12:13], v[12:13], v[144:145]
	v_pk_mul_f32 v[14:15], v[14:15], v[146:147]
	v_cvt_pk_fp8_f32 v6, v8, v9
	v_cvt_pk_fp8_f32 v7, v12, v13
	v_cvt_pk_fp8_f32 v6, v10, v11 op_sel:[0,0,1]
	v_cvt_pk_fp8_f32 v7, v14, v15 op_sel:[0,0,1]
	s_nop 0
	global_store_dwordx2 v4, v[6:7], s[24:25]
	v_add_u32_e32 v4, 0xb000, v4
	v_pk_mul_f32 v[8:9], v[140:141], s[98:99] op_sel:[0,1] op_sel_hi:[1,1]
	v_pk_mul_f32 v[10:11], v[142:143], s[98:99] op_sel:[0,1] op_sel_hi:[1,1]
	v_pk_mul_f32 v[12:13], v[136:137], s[98:99] op_sel:[0,1] op_sel_hi:[1,1]
	v_pk_mul_f32 v[14:15], v[138:139], s[98:99] op_sel:[0,1] op_sel_hi:[1,1]
	v_exp_f32_e32 v8, v8
	v_exp_f32_e32 v9, v9
	v_exp_f32_e32 v10, v10
	v_exp_f32_e32 v11, v11
	v_exp_f32_e32 v12, v12
	v_exp_f32_e32 v13, v13
	v_exp_f32_e32 v14, v14
	v_exp_f32_e32 v15, v15
	v_pk_fma_f32 v[8:9], v[8:9], s[98:99], s[98:99] op_sel_hi:[1,0,0]
	v_pk_fma_f32 v[10:11], v[10:11], s[98:99], s[98:99] op_sel_hi:[1,0,0]
	v_pk_fma_f32 v[12:13], v[12:13], s[98:99], s[98:99] op_sel_hi:[1,0,0]
	v_pk_fma_f32 v[14:15], v[14:15], s[98:99], s[98:99] op_sel_hi:[1,0,0]
	v_rcp_f32_e32 v8, v8
	v_rcp_f32_e32 v9, v9
	v_rcp_f32_e32 v10, v10
	v_rcp_f32_e32 v11, v11
	v_rcp_f32_e32 v12, v12
	v_rcp_f32_e32 v13, v13
	v_rcp_f32_e32 v14, v14
	v_rcp_f32_e32 v15, v15
	v_pk_mul_f32 v[8:9], v[140:141], v[8:9]
	v_pk_mul_f32 v[10:11], v[142:143], v[10:11]
	v_pk_mul_f32 v[12:13], v[136:137], v[12:13]
	v_pk_mul_f32 v[14:15], v[138:139], v[14:15]
	v_pk_mul_f32 v[8:9], v[8:9], v[132:133]
	v_pk_mul_f32 v[10:11], v[10:11], v[134:135]
	v_pk_mul_f32 v[12:13], v[12:13], v[128:129]
	v_pk_mul_f32 v[14:15], v[14:15], v[130:131]
	v_cvt_pk_fp8_f32 v6, v8, v9
	v_cvt_pk_fp8_f32 v7, v12, v13
	v_cvt_pk_fp8_f32 v6, v10, v11 op_sel:[0,0,1]
	v_cvt_pk_fp8_f32 v7, v14, v15 op_sel:[0,0,1]
	s_nop 0
	global_store_dwordx2 v4, v[6:7], s[24:25]
	v_add_u32_e32 v4, 0xb000, v4
	v_pk_mul_f32 v[8:9], v[124:125], s[98:99] op_sel:[0,1] op_sel_hi:[1,1]
	v_pk_mul_f32 v[10:11], v[126:127], s[98:99] op_sel:[0,1] op_sel_hi:[1,1]
	v_pk_mul_f32 v[12:13], v[120:121], s[98:99] op_sel:[0,1] op_sel_hi:[1,1]
	v_pk_mul_f32 v[14:15], v[122:123], s[98:99] op_sel:[0,1] op_sel_hi:[1,1]
	v_exp_f32_e32 v8, v8
	v_exp_f32_e32 v9, v9
	v_exp_f32_e32 v10, v10
	v_exp_f32_e32 v11, v11
	v_exp_f32_e32 v12, v12
	v_exp_f32_e32 v13, v13
	v_exp_f32_e32 v14, v14
	v_exp_f32_e32 v15, v15
	v_pk_fma_f32 v[8:9], v[8:9], s[98:99], s[98:99] op_sel_hi:[1,0,0]
	v_pk_fma_f32 v[10:11], v[10:11], s[98:99], s[98:99] op_sel_hi:[1,0,0]
	v_pk_fma_f32 v[12:13], v[12:13], s[98:99], s[98:99] op_sel_hi:[1,0,0]
	v_pk_fma_f32 v[14:15], v[14:15], s[98:99], s[98:99] op_sel_hi:[1,0,0]
	v_rcp_f32_e32 v8, v8
	v_rcp_f32_e32 v9, v9
	v_rcp_f32_e32 v10, v10
	v_rcp_f32_e32 v11, v11
	v_rcp_f32_e32 v12, v12
	v_rcp_f32_e32 v13, v13
	v_rcp_f32_e32 v14, v14
	v_rcp_f32_e32 v15, v15
	v_pk_mul_f32 v[8:9], v[124:125], v[8:9]
	v_pk_mul_f32 v[10:11], v[126:127], v[10:11]
	v_pk_mul_f32 v[12:13], v[120:121], v[12:13]
	v_pk_mul_f32 v[14:15], v[122:123], v[14:15]
	v_pk_mul_f32 v[8:9], v[8:9], v[116:117]
	v_pk_mul_f32 v[10:11], v[10:11], v[118:119]
	v_pk_mul_f32 v[12:13], v[12:13], v[112:113]
	v_pk_mul_f32 v[14:15], v[14:15], v[114:115]
	v_cvt_pk_fp8_f32 v6, v8, v9
	v_cvt_pk_fp8_f32 v7, v12, v13
	v_cvt_pk_fp8_f32 v6, v10, v11 op_sel:[0,0,1]
	v_cvt_pk_fp8_f32 v7, v14, v15 op_sel:[0,0,1]
	s_nop 0
	global_store_dwordx2 v4, v[6:7], s[24:25]
	v_add_u32_e32 v4, 0xb000, v4
	v_pk_mul_f32 v[8:9], v[108:109], s[98:99] op_sel:[0,1] op_sel_hi:[1,1]
	v_pk_mul_f32 v[10:11], v[110:111], s[98:99] op_sel:[0,1] op_sel_hi:[1,1]
	v_pk_mul_f32 v[12:13], v[104:105], s[98:99] op_sel:[0,1] op_sel_hi:[1,1]
	v_pk_mul_f32 v[14:15], v[106:107], s[98:99] op_sel:[0,1] op_sel_hi:[1,1]
	v_exp_f32_e32 v8, v8
	v_exp_f32_e32 v9, v9
	v_exp_f32_e32 v10, v10
	v_exp_f32_e32 v11, v11
	v_exp_f32_e32 v12, v12
	v_exp_f32_e32 v13, v13
	v_exp_f32_e32 v14, v14
	v_exp_f32_e32 v15, v15
	v_pk_fma_f32 v[8:9], v[8:9], s[98:99], s[98:99] op_sel_hi:[1,0,0]
	v_pk_fma_f32 v[10:11], v[10:11], s[98:99], s[98:99] op_sel_hi:[1,0,0]
	v_pk_fma_f32 v[12:13], v[12:13], s[98:99], s[98:99] op_sel_hi:[1,0,0]
	v_pk_fma_f32 v[14:15], v[14:15], s[98:99], s[98:99] op_sel_hi:[1,0,0]
	v_rcp_f32_e32 v8, v8
	v_rcp_f32_e32 v9, v9
	v_rcp_f32_e32 v10, v10
	v_rcp_f32_e32 v11, v11
	v_rcp_f32_e32 v12, v12
	v_rcp_f32_e32 v13, v13
	v_rcp_f32_e32 v14, v14
	v_rcp_f32_e32 v15, v15
	v_pk_mul_f32 v[8:9], v[108:109], v[8:9]
	v_pk_mul_f32 v[10:11], v[110:111], v[10:11]
	v_pk_mul_f32 v[12:13], v[104:105], v[12:13]
	v_pk_mul_f32 v[14:15], v[106:107], v[14:15]
	v_pk_mul_f32 v[8:9], v[8:9], v[100:101]
	v_pk_mul_f32 v[10:11], v[10:11], v[102:103]
	v_pk_mul_f32 v[12:13], v[12:13], v[96:97]
	v_pk_mul_f32 v[14:15], v[14:15], v[98:99]
	v_cvt_pk_fp8_f32 v6, v8, v9
	v_cvt_pk_fp8_f32 v7, v12, v13
	v_cvt_pk_fp8_f32 v6, v10, v11 op_sel:[0,0,1]
	v_cvt_pk_fp8_f32 v7, v14, v15 op_sel:[0,0,1]
	s_nop 0
	global_store_dwordx2 v4, v[6:7], s[24:25]
	v_add_u32_e32 v4, 0x37000, v4
	v_pk_mul_f32 v[8:9], v[92:93], s[98:99] op_sel:[0,1] op_sel_hi:[1,1]
	v_pk_mul_f32 v[10:11], v[94:95], s[98:99] op_sel:[0,1] op_sel_hi:[1,1]
	v_pk_mul_f32 v[12:13], v[88:89], s[98:99] op_sel:[0,1] op_sel_hi:[1,1]
	v_pk_mul_f32 v[14:15], v[90:91], s[98:99] op_sel:[0,1] op_sel_hi:[1,1]
	v_exp_f32_e32 v8, v8
	v_exp_f32_e32 v9, v9
	v_exp_f32_e32 v10, v10
	v_exp_f32_e32 v11, v11
	v_exp_f32_e32 v12, v12
	v_exp_f32_e32 v13, v13
	v_exp_f32_e32 v14, v14
	v_exp_f32_e32 v15, v15
	v_pk_fma_f32 v[8:9], v[8:9], s[98:99], s[98:99] op_sel_hi:[1,0,0]
	v_pk_fma_f32 v[10:11], v[10:11], s[98:99], s[98:99] op_sel_hi:[1,0,0]
	v_pk_fma_f32 v[12:13], v[12:13], s[98:99], s[98:99] op_sel_hi:[1,0,0]
	v_pk_fma_f32 v[14:15], v[14:15], s[98:99], s[98:99] op_sel_hi:[1,0,0]
	v_rcp_f32_e32 v8, v8
	v_rcp_f32_e32 v9, v9
	v_rcp_f32_e32 v10, v10
	v_rcp_f32_e32 v11, v11
	v_rcp_f32_e32 v12, v12
	v_rcp_f32_e32 v13, v13
	v_rcp_f32_e32 v14, v14
	v_rcp_f32_e32 v15, v15
	v_pk_mul_f32 v[8:9], v[92:93], v[8:9]
	v_pk_mul_f32 v[10:11], v[94:95], v[10:11]
	v_pk_mul_f32 v[12:13], v[88:89], v[12:13]
	v_pk_mul_f32 v[14:15], v[90:91], v[14:15]
	v_pk_mul_f32 v[8:9], v[8:9], v[84:85]
	v_pk_mul_f32 v[10:11], v[10:11], v[86:87]
	v_pk_mul_f32 v[12:13], v[12:13], v[80:81]
	v_pk_mul_f32 v[14:15], v[14:15], v[82:83]
	v_cvt_pk_fp8_f32 v6, v8, v9
	v_cvt_pk_fp8_f32 v7, v12, v13
	v_cvt_pk_fp8_f32 v6, v10, v11 op_sel:[0,0,1]
	v_cvt_pk_fp8_f32 v7, v14, v15 op_sel:[0,0,1]
	s_nop 0
	global_store_dwordx2 v4, v[6:7], s[24:25]
	v_add_u32_e32 v4, 0xb000, v4
	v_pk_mul_f32 v[8:9], v[76:77], s[98:99] op_sel:[0,1] op_sel_hi:[1,1]
	v_pk_mul_f32 v[10:11], v[78:79], s[98:99] op_sel:[0,1] op_sel_hi:[1,1]
	v_pk_mul_f32 v[12:13], v[72:73], s[98:99] op_sel:[0,1] op_sel_hi:[1,1]
	v_pk_mul_f32 v[14:15], v[74:75], s[98:99] op_sel:[0,1] op_sel_hi:[1,1]
	v_exp_f32_e32 v8, v8
	v_exp_f32_e32 v9, v9
	v_exp_f32_e32 v10, v10
	v_exp_f32_e32 v11, v11
	v_exp_f32_e32 v12, v12
	v_exp_f32_e32 v13, v13
	v_exp_f32_e32 v14, v14
	v_exp_f32_e32 v15, v15
	v_pk_fma_f32 v[8:9], v[8:9], s[98:99], s[98:99] op_sel_hi:[1,0,0]
	v_pk_fma_f32 v[10:11], v[10:11], s[98:99], s[98:99] op_sel_hi:[1,0,0]
	v_pk_fma_f32 v[12:13], v[12:13], s[98:99], s[98:99] op_sel_hi:[1,0,0]
	v_pk_fma_f32 v[14:15], v[14:15], s[98:99], s[98:99] op_sel_hi:[1,0,0]
	v_rcp_f32_e32 v8, v8
	v_rcp_f32_e32 v9, v9
	v_rcp_f32_e32 v10, v10
	v_rcp_f32_e32 v11, v11
	v_rcp_f32_e32 v12, v12
	v_rcp_f32_e32 v13, v13
	v_rcp_f32_e32 v14, v14
	v_rcp_f32_e32 v15, v15
	v_pk_mul_f32 v[8:9], v[76:77], v[8:9]
	v_pk_mul_f32 v[10:11], v[78:79], v[10:11]
	v_pk_mul_f32 v[12:13], v[72:73], v[12:13]
	v_pk_mul_f32 v[14:15], v[74:75], v[14:15]
	v_pk_mul_f32 v[8:9], v[8:9], v[68:69]
	v_pk_mul_f32 v[10:11], v[10:11], v[70:71]
	v_pk_mul_f32 v[12:13], v[12:13], v[64:65]
	v_pk_mul_f32 v[14:15], v[14:15], v[66:67]
	v_cvt_pk_fp8_f32 v6, v8, v9
	v_cvt_pk_fp8_f32 v7, v12, v13
	v_cvt_pk_fp8_f32 v6, v10, v11 op_sel:[0,0,1]
	v_cvt_pk_fp8_f32 v7, v14, v15 op_sel:[0,0,1]
	s_nop 0
	global_store_dwordx2 v4, v[6:7], s[24:25]
	v_add_u32_e32 v4, 0xb000, v4
	v_pk_mul_f32 v[8:9], v[60:61], s[98:99] op_sel:[0,1] op_sel_hi:[1,1]
	v_pk_mul_f32 v[10:11], v[62:63], s[98:99] op_sel:[0,1] op_sel_hi:[1,1]
	v_pk_mul_f32 v[12:13], v[56:57], s[98:99] op_sel:[0,1] op_sel_hi:[1,1]
	v_pk_mul_f32 v[14:15], v[58:59], s[98:99] op_sel:[0,1] op_sel_hi:[1,1]
	v_exp_f32_e32 v8, v8
	v_exp_f32_e32 v9, v9
	v_exp_f32_e32 v10, v10
	v_exp_f32_e32 v11, v11
	v_exp_f32_e32 v12, v12
	v_exp_f32_e32 v13, v13
	v_exp_f32_e32 v14, v14
	v_exp_f32_e32 v15, v15
	v_pk_fma_f32 v[8:9], v[8:9], s[98:99], s[98:99] op_sel_hi:[1,0,0]
	v_pk_fma_f32 v[10:11], v[10:11], s[98:99], s[98:99] op_sel_hi:[1,0,0]
	v_pk_fma_f32 v[12:13], v[12:13], s[98:99], s[98:99] op_sel_hi:[1,0,0]
	v_pk_fma_f32 v[14:15], v[14:15], s[98:99], s[98:99] op_sel_hi:[1,0,0]
	v_rcp_f32_e32 v8, v8
	v_rcp_f32_e32 v9, v9
	v_rcp_f32_e32 v10, v10
	v_rcp_f32_e32 v11, v11
	v_rcp_f32_e32 v12, v12
	v_rcp_f32_e32 v13, v13
	v_rcp_f32_e32 v14, v14
	v_rcp_f32_e32 v15, v15
	v_pk_mul_f32 v[8:9], v[60:61], v[8:9]
	v_pk_mul_f32 v[10:11], v[62:63], v[10:11]
	v_pk_mul_f32 v[12:13], v[56:57], v[12:13]
	v_pk_mul_f32 v[14:15], v[58:59], v[14:15]
	v_pk_mul_f32 v[8:9], v[8:9], v[52:53]
	v_pk_mul_f32 v[10:11], v[10:11], v[54:55]
	v_pk_mul_f32 v[12:13], v[12:13], v[48:49]
	v_pk_mul_f32 v[14:15], v[14:15], v[50:51]
	v_cvt_pk_fp8_f32 v6, v8, v9
	v_cvt_pk_fp8_f32 v7, v12, v13
	v_cvt_pk_fp8_f32 v6, v10, v11 op_sel:[0,0,1]
	v_cvt_pk_fp8_f32 v7, v14, v15 op_sel:[0,0,1]
	s_nop 0
	global_store_dwordx2 v4, v[6:7], s[24:25]
	v_add_u32_e32 v4, 0xb000, v4
	v_pk_mul_f32 v[8:9], v[44:45], s[98:99] op_sel:[0,1] op_sel_hi:[1,1]
	v_pk_mul_f32 v[10:11], v[46:47], s[98:99] op_sel:[0,1] op_sel_hi:[1,1]
	v_pk_mul_f32 v[12:13], v[40:41], s[98:99] op_sel:[0,1] op_sel_hi:[1,1]
	v_pk_mul_f32 v[14:15], v[42:43], s[98:99] op_sel:[0,1] op_sel_hi:[1,1]
	v_exp_f32_e32 v8, v8
	v_exp_f32_e32 v9, v9
	v_exp_f32_e32 v10, v10
	v_exp_f32_e32 v11, v11
	v_exp_f32_e32 v12, v12
	v_exp_f32_e32 v13, v13
	v_exp_f32_e32 v14, v14
	v_exp_f32_e32 v15, v15
	v_pk_fma_f32 v[8:9], v[8:9], s[98:99], s[98:99] op_sel_hi:[1,0,0]
	v_pk_fma_f32 v[10:11], v[10:11], s[98:99], s[98:99] op_sel_hi:[1,0,0]
	v_pk_fma_f32 v[12:13], v[12:13], s[98:99], s[98:99] op_sel_hi:[1,0,0]
	v_pk_fma_f32 v[14:15], v[14:15], s[98:99], s[98:99] op_sel_hi:[1,0,0]
	v_rcp_f32_e32 v8, v8
	v_rcp_f32_e32 v9, v9
	v_rcp_f32_e32 v10, v10
	v_rcp_f32_e32 v11, v11
	v_rcp_f32_e32 v12, v12
	v_rcp_f32_e32 v13, v13
	v_rcp_f32_e32 v14, v14
	v_rcp_f32_e32 v15, v15
	v_pk_mul_f32 v[8:9], v[44:45], v[8:9]
	v_pk_mul_f32 v[10:11], v[46:47], v[10:11]
	v_pk_mul_f32 v[12:13], v[40:41], v[12:13]
	v_pk_mul_f32 v[14:15], v[42:43], v[14:15]
	v_pk_mul_f32 v[8:9], v[8:9], v[36:37]
	v_pk_mul_f32 v[10:11], v[10:11], v[38:39]
	v_pk_mul_f32 v[12:13], v[12:13], v[32:33]
	v_pk_mul_f32 v[14:15], v[14:15], v[34:35]
	v_cvt_pk_fp8_f32 v6, v8, v9
	v_cvt_pk_fp8_f32 v7, v12, v13
	v_cvt_pk_fp8_f32 v6, v10, v11 op_sel:[0,0,1]
	v_cvt_pk_fp8_f32 v7, v14, v15 op_sel:[0,0,1]
	s_nop 0
	global_store_dwordx2 v4, v[6:7], s[24:25]
	s_andn2_b64 vcc, exec, s[18:19]
	s_mov_b64 s[18:19], -1
	s_cbranch_vccnz .LBB0_1244
	s_andn2_b64 vcc, exec, s[8:9]
	s_cbranch_vccnz .LBB0_1243
	s_barrier
	s_branch .LBB0_1243
